# stack2 + G3 next-unit tile touch-prefetch into L2
# speedup vs baseline: 1.0025x; 1.0025x over previous
; __device__ __forceinline__ void gla_g3(LAS unsigned char* lds, const bf16_t* P, const bf16_t* VAT, const bf16_t* DS, const float* BC, const float* gn, bf16_t* MIX) {
;     ...
;         const int c = uid & 31, h = (uid >> 5) & 3, bl = uid >> 7;
;         const size_t row0 = (size_t)bl * SEQ + c * 64, qrow = row0 + iq;
;         bf16x8 qraw[2]; f32x4 gvv[4]; u32x2 rvv[4];
; #pragma unroll
;         for (int s2 = 0; s2 < 2; ++s2) qraw[s2] = *(const bf16x8*)(P + qrow * 2048 + h * 64 + 32 * s2 + 8 * g);
; #pragma unroll
;         for (int mb = 0; mb < 4; ++mb) { const int cc = h * 128 + 16 * (4 * dvh + mb) + 4 * g; gvv[mb] = *(const f32x4*)(gn + cc); rvv[mb] = *(const u32x2*)(P + qrow * 2048 + 512 + cc); }
;         asm volatile("s_waitcnt vmcnt(0)" ::: "memory");
;         __syncthreads();
;         {
;             const int j = 8 * wv + (lane >> 3), ch = lane & 7;
;             const bf16x8 kr = *(const LAS bf16x8*)(lds + G3_KRAW + (j * 9 + ch) * 16);
;             const LAS float* tf = (const LAS float*)(lds + G3_TBF + j * 272 + ch * 32); const LAS float* tb = (const LAS float*)(lds + G3_TBB + j * 272 + ch * 32);
;             f32x4 a0 = *(const LAS f32x4*)tf, a1 = *(const LAS f32x4*)(tf + 4), b0 = *(const LAS f32x4*)tb, b1 = *(const LAS f32x4*)(tb + 4);
; #pragma unroll
;             for (int q = 0; q < 4; ++q) { a0[q] = __builtin_amdgcn_exp2f(-a0[q]); a1[q] = __builtin_amdgcn_exp2f(-a1[q]); b0[q] = __builtin_amdgcn_exp2f(-b0[q]); b1[q] = __builtin_amdgcn_exp2f(-b1[q]); }
;             *(LAS bf16x8*)(lds + G3_KIF + (j * 9 + ch) * 16) = scale8(kr, a0, a1); *(LAS bf16x8*)(lds + G3_KIB + (j * 9 + ch) * 16) = scale8(kr, b0, b1);
;         }
;         bf16x8 qdf[2], qdb[2];
; #pragma unroll
;         for (int s2 = 0; s2 < 2; ++s2) {
;             const LAS float* tf = (const LAS float*)(lds + G3_TBF + iq * 272 + (32 * s2 + 8 * g) * 4); const LAS float* tb = (const LAS float*)(lds + G3_TBB + iq * 272 + (32 * s2 + 8 * g) * 4);
;             f32x4 a0 = *(const LAS f32x4*)tf, a1 = *(const LAS f32x4*)(tf + 4), b0 = *(const LAS f32x4*)tb, b1 = *(const LAS f32x4*)(tb + 4);
; #pragma unroll
;             for (int q = 0; q < 4; ++q) { a0[q] = __builtin_amdgcn_exp2f(a0[q]); a1[q] = __builtin_amdgcn_exp2f(a1[q]); b0[q] = __builtin_amdgcn_exp2f(b0[q]); b1[q] = __builtin_amdgcn_exp2f(b1[q]); }
;             qdf[s2] = scale8(qraw[s2], a0, a1); qdb[s2] = scale8(qraw[s2], b0, b1);
.LBB0_629:
	s_ashr_i32 s0, s94, 7
	s_ashr_i32 s1, s0, 31
	s_lshl_b32 s2, s94, 6
	s_lshl_b64 s[0:1], s[0:1], 11
	s_and_b32 s2, s2, 0x7c0
	s_or_b32 s0, s0, s2
	v_mov_b32_e32 v49, s1
	v_or_b32_e32 v48, s0, v36
	v_lshlrev_b64 v[0:1], 12, v[48:49]
	s_lshl_b32 s0, s94, 2
	v_lshl_add_u64 v[0:1], s[24:25], 0, v[0:1]
	s_and_b32 s2, s0, 0x180
	v_lshl_add_u64 v[2:3], v[0:1], 0, s[2:3]
	v_lshl_add_u64 v[2:3], v[2:3], 0, v[190:191]
	global_load_dwordx4 v[20:23], v[2:3], off
	global_load_dwordx4 v[16:19], v[2:3], off offset:64
	v_add_u32_e32 v44, s2, v50
	v_ashrrev_i32_e32 v45, 31, v44
	v_lshl_add_u64 v[2:3], v[44:45], 2, s[80:81]
	v_lshl_add_u64 v[24:25], v[44:45], 1, v[0:1]
	global_load_dwordx4 v[12:15], v[2:3], off
	global_load_dwordx2 v[46:47], v[24:25], off offset:1024
	global_load_dwordx4 v[8:11], v[2:3], off offset:64
	global_load_dwordx2 v[42:43], v[24:25], off offset:1056
	global_load_dwordx4 v[4:7], v[2:3], off offset:128
	global_load_dwordx2 v[40:41], v[24:25], off offset:1088
	s_nop 0
	global_load_dwordx4 v[0:3], v[2:3], off offset:192
	s_nop 0
	global_load_dwordx2 v[38:39], v[24:25], off offset:1120
	v_add_u32_e32 v24, 0, v51
	s_waitcnt vmcnt(0)
	s_waitcnt vmcnt(0) lgkmcnt(0)
	s_barrier
	s_add_i32 s98, s94, s92
	s_cmpk_gt_i32 s98, 0xbff
	s_cbranch_scc1 .Lg3_touch_done
	v_lshrrev_b32_e32 v100, 6, v250
	v_and_b32_e32 v101, 63, v250
	s_mov_b32 m0, 0x20000
	v_mov_b32_e32 v105, 0
	v_readfirstlane_b32 s99, v100
	v_and_b32_e32 v103, 3, v100
	v_lshlrev_b32_e32 v104, 7, v101
	v_lshl_add_u32 v104, v103, 13, v104
	s_lshl_b32 s100, s98, 15
	v_add_u32_e32 v104, s100, v104
	s_cmp_lt_u32 s99, 4
	s_cbranch_scc0 .Lg3_touch_bc
	v_lshl_add_u64 v[106:107], s[36:37], 0, v[104:105]
	s_branch .Lg3_touch_c
.Lg3_touch_bc:
	v_readlane_b32 s100, v253, 15
	v_readlane_b32 s101, v253, 16
	s_nop 1
	v_lshl_add_u64 v[106:107], s[100:101], 0, v[104:105]
.Lg3_touch_c:
	global_load_lds_dword v[106:107], off
	s_cmp_gt_u32 s99, 2
	s_cbranch_scc1 .Lg3_touch_done
	s_cmp_eq_u32 s99, 0
	s_cbranch_scc0 .Lg3_touch_vt
	s_lshr_b32 s100, s98, 7
	s_lshl_b32 s100, s100, 11
	s_and_b32 s101, s98, 31
	s_lshl_b32 s101, s101, 6
	s_or_b32 s100, s100, s101
	s_bfe_u32 s101, s98, 0x20005
	s_lshl_b32 s101, s101, 7
	s_addk_i32 s101, 0x200
	v_add_u32_e32 v104, s100, v101
	v_lshlrev_b32_e32 v104, 12, v104
	v_add_u32_e32 v104, s101, v104
	v_lshl_add_u64 v[106:107], s[24:25], 0, v[104:105]
	global_load_lds_dword v[106:107], off
	s_branch .Lg3_touch_done
.Lg3_touch_vt:
	s_lshr_b32 s100, s98, 5
	s_lshl_b32 s100, s100, 7
	s_add_i32 s101, s99, -1
	s_lshl_b32 s101, s101, 6
	s_add_i32 s100, s100, s101
	s_and_b32 s101, s98, 31
	s_lshl_b32 s101, s101, 7
	v_add_u32_e32 v104, s100, v101
	v_lshlrev_b32_e32 v104, 12, v104
	v_add_u32_e32 v104, s101, v104
	v_readlane_b32 s100, v253, 7
	v_readlane_b32 s101, v253, 8
	s_nop 1
	v_lshl_add_u64 v[106:107], s[100:101], 0, v[104:105]
	global_load_lds_dword v[106:107], off
.Lg3_touch_done:
	ds_read_b128 v[24:27], v24
	ds_read_b128 v[28:31], v57 offset:64512
	ds_read_b128 v[32:35], v57 offset:64528
	ds_read_b128 v[70:73], v58
	ds_read_b128 v[74:77], v58 offset:16
	s_waitcnt lgkmcnt(4)
	v_lshlrev_b32_e32 v78, 16, v24
	s_waitcnt lgkmcnt(3)
	v_exp_f32_e64 v28, -v28
	v_exp_f32_e64 v29, -v29
	v_exp_f32_e64 v30, -v30
	v_exp_f32_e64 v31, -v31
	v_and_b32_e32 v79, 0xffff0000, v24
	s_waitcnt lgkmcnt(2)
	v_exp_f32_e64 v32, -v32
	v_exp_f32_e64 v33, -v33
	v_pk_mul_f32 v[28:29], v[28:29], v[78:79]
	v_exp_f32_e64 v34, -v34
	v_cvt_pk_bf16_f32 v24, v28, v29
	v_lshlrev_b32_e32 v28, 16, v25
	v_and_b32_e32 v29, 0xffff0000, v25
	v_exp_f32_e64 v35, -v35
	v_pk_mul_f32 v[30:31], v[30:31], v[28:29]
	s_waitcnt lgkmcnt(1)
	v_exp_f32_e64 v70, -v70
	v_cvt_pk_bf16_f32 v25, v30, v31
	v_lshlrev_b32_e32 v30, 16, v26
	v_and_b32_e32 v31, 0xffff0000, v26
	v_exp_f32_e64 v71, -v71
	v_exp_f32_e64 v72, -v72
	v_exp_f32_e64 v73, -v73
	v_pk_mul_f32 v[32:33], v[32:33], v[30:31]
	s_waitcnt lgkmcnt(0)
	v_exp_f32_e64 v74, -v74
	v_exp_f32_e64 v75, -v75
	v_exp_f32_e64 v76, -v76
	v_exp_f32_e64 v77, -v77
	v_cvt_pk_bf16_f32 v26, v32, v33
	v_lshlrev_b32_e32 v32, 16, v27
	v_and_b32_e32 v33, 0xffff0000, v27
	v_pk_mul_f32 v[34:35], v[34:35], v[32:33]
	v_readlane_b32 s0, v254, 34
	v_cvt_pk_bf16_f32 v27, v34, v35
	v_add_u32_e32 v34, s35, v51
	ds_write_b128 v34, v[24:27]
	v_pk_mul_f32 v[24:25], v[70:71], v[78:79]
	v_pk_mul_f32 v[26:27], v[72:73], v[28:29]
	v_cvt_pk_bf16_f32 v24, v24, v25
	v_cvt_pk_bf16_f32 v25, v26, v27
	v_pk_mul_f32 v[26:27], v[74:75], v[30:31]
	v_pk_mul_f32 v[28:29], v[76:77], v[32:33]
	v_cvt_pk_bf16_f32 v26, v26, v27
	v_cvt_pk_bf16_f32 v27, v28, v29
	v_add_u32_e32 v28, s0, v51
	ds_write_b128 v28, v[24:27]
	ds_read_b128 v[24:27], v59 offset:64512
	ds_read_b128 v[28:31], v59 offset:64528
	ds_read_b128 v[32:35], v60
	ds_read_b128 v[70:73], v60 offset:16
	v_add_u32_e32 v69, s35, v53
	s_waitcnt lgkmcnt(3)
	v_exp_f32_e32 v24, v24
	v_exp_f32_e32 v25, v25
	s_waitcnt lgkmcnt(1)
	v_exp_f32_e32 v32, v32
	v_exp_f32_e32 v33, v33
	v_exp_f32_e32 v26, v26
	v_exp_f32_e32 v27, v27
	v_exp_f32_e32 v34, v34
	v_exp_f32_e32 v35, v35
	v_exp_f32_e32 v28, v28
	v_exp_f32_e32 v29, v29
	s_waitcnt lgkmcnt(0)
; #define LAS __attribute__((address_space(3)))
; __device__ __forceinline__ u32x4 pack8(const f32x4 a, const f32x4 b) { u32x4 w; w.x = cvt_pk_bf16(a[0], a[1]); w.y = cvt_pk_bf16(a[2], a[3]); w.z = cvt_pk_bf16(b[0], b[1]); w.w = cvt_pk_bf16(b[2], b[3]); return w; }
; __device__ __forceinline__ f32x4 mfma16(bf16x8 a, bf16x8 b, f32x4 c) { return __builtin_amdgcn_mfma_f32_16x16x32_bf16(a, b, c, 0, 0, 0); }
; __device__ __forceinline__ void gla_g3(LAS unsigned char* lds, const bf16_t* P, const bf16_t* VAT, const bf16_t* DS, const float* BC, const float* gn, bf16_t* MIX) {
;     ...
; #pragma unroll
;         for (int s2 = 0; s2 < 2; ++s2) {
;             const LAS float* tf = (const LAS float*)(lds + G3_TBF + iq * 272 + (32 * s2 + 8 * g) * 4); const LAS float* tb = (const LAS float*)(lds + G3_TBB + iq * 272 + (32 * s2 + 8 * g) * 4);
;             f32x4 a0 = *(const LAS f32x4*)tf, a1 = *(const LAS f32x4*)(tf + 4), b0 = *(const LAS f32x4*)tb, b1 = *(const LAS f32x4*)(tb + 4);
; #pragma unroll
;             for (int q = 0; q < 4; ++q) { a0[q] = __builtin_amdgcn_exp2f(a0[q]); a1[q] = __builtin_amdgcn_exp2f(a1[q]); b0[q] = __builtin_amdgcn_exp2f(b0[q]); b1[q] = __builtin_amdgcn_exp2f(b1[q]); }
;             qdf[s2] = scale8(qraw[s2], a0, a1); qdb[s2] = scale8(qraw[s2], b0, b1);
;         }
;         __syncthreads();
;         bf16x8 pfrag[2];
; #pragma unroll
;         for (int t = 0; t < 2; ++t) {
;             f32x4 sf[2], sv[2];
; #pragma unroll
;             for (int u = 0; u < 2; ++u) {
;                 const int j = 32 * t + 8 * (fr >> 2) + 4 * u + (fr & 3);
;                 sf[u] = (f32x4){0.f, 0.f, 0.f, 0.f}; sv[u] = (f32x4){0.f, 0.f, 0.f, 0.f};
; #pragma unroll
;                 for (int s2 = 0; s2 < 2; ++s2) {
;                     sf[u] = mfma16(*(const LAS bf16x8*)(lds + G3_KIF + (j * 9 + 4 * s2 + g) * 16), qdf[s2], sf[u]);
;                     sv[u] = mfma16(*(const LAS bf16x8*)(lds + G3_KIB + (j * 9 + 4 * s2 + g) * 16), qdb[s2], sv[u]);
;                 }
;             }
;             f32x4 p0, p1;
; #pragma unroll
;             for (int ii = 0; ii < 4; ++ii) { const int j0 = 32 * t + 8 * g + ii, j1 = j0 + 4; p0[ii] = (j0 <= iq) ? sf[0][ii] : sv[0][ii]; p1[ii] = (j1 <= iq) ? sf[1][ii] : sv[1][ii]; }
;             pfrag[t] = __builtin_bit_cast(bf16x8, pack8(p0, p1));
	v_exp_f32_e32 v70, v70
	v_exp_f32_e32 v71, v71
	v_exp_f32_e32 v30, v30
	v_exp_f32_e32 v72, v72
	v_exp_f32_e32 v31, v31
	v_exp_f32_e32 v73, v73
	v_add_u32_e32 v86, s0, v54
	v_add_u32_e32 v90, s0, v56
	v_lshlrev_b32_e32 v74, 16, v20
	v_and_b32_e32 v75, 0xffff0000, v20
	v_pk_mul_f32 v[24:25], v[24:25], v[74:75]
	v_lshlrev_b32_e32 v78, 16, v16
	v_cvt_pk_bf16_f32 v20, v24, v25
	v_pk_mul_f32 v[24:25], v[32:33], v[74:75]
	v_lshlrev_b32_e32 v32, 16, v21
	v_and_b32_e32 v33, 0xffff0000, v21
	v_pk_mul_f32 v[26:27], v[26:27], v[32:33]
	v_cvt_pk_bf16_f32 v24, v24, v25
	v_cvt_pk_bf16_f32 v21, v26, v27
	v_pk_mul_f32 v[26:27], v[34:35], v[32:33]
	v_and_b32_e32 v79, 0xffff0000, v16
	v_cvt_pk_bf16_f32 v25, v26, v27
	v_lshlrev_b32_e32 v26, 16, v22
	v_and_b32_e32 v27, 0xffff0000, v22
	v_pk_mul_f32 v[28:29], v[28:29], v[26:27]
	v_pk_mul_f32 v[26:27], v[70:71], v[26:27]
	v_cvt_pk_bf16_f32 v22, v28, v29
	v_lshlrev_b32_e32 v28, 16, v23
	v_and_b32_e32 v29, 0xffff0000, v23
	v_pk_mul_f32 v[30:31], v[30:31], v[28:29]
	v_pk_mul_f32 v[28:29], v[72:73], v[28:29]
	v_cvt_pk_bf16_f32 v26, v26, v27
	v_cvt_pk_bf16_f32 v23, v30, v31
	v_cvt_pk_bf16_f32 v27, v28, v29
	ds_read_b128 v[28:31], v59 offset:64640
	ds_read_b128 v[32:35], v59 offset:64656
	ds_read_b128 v[70:73], v60 offset:128
	ds_read_b128 v[74:77], v60 offset:144
	s_waitcnt lgkmcnt(0)
	v_exp_f32_e32 v28, v28
	v_exp_f32_e32 v29, v29
	v_exp_f32_e32 v70, v70
	v_exp_f32_e32 v71, v71
	v_exp_f32_e32 v30, v30
	v_exp_f32_e32 v31, v31
	v_exp_f32_e32 v72, v72
	v_exp_f32_e32 v73, v73
	v_exp_f32_e32 v32, v32
	v_exp_f32_e32 v74, v74
	v_exp_f32_e32 v33, v33
	v_exp_f32_e32 v75, v75
	v_pk_mul_f32 v[70:71], v[70:71], v[78:79]
	v_exp_f32_e32 v34, v34
	v_cvt_pk_bf16_f32 v16, v70, v71
	v_lshlrev_b32_e32 v70, 16, v17
	v_and_b32_e32 v71, 0xffff0000, v17
	v_exp_f32_e32 v76, v76
	v_exp_f32_e32 v35, v35
	v_exp_f32_e32 v77, v77
	v_pk_mul_f32 v[28:29], v[28:29], v[78:79]
	v_pk_mul_f32 v[30:31], v[30:31], v[70:71]
	v_cvt_pk_bf16_f32 v28, v28, v29
	v_cvt_pk_bf16_f32 v29, v30, v31
	v_pk_mul_f32 v[30:31], v[72:73], v[70:71]
	v_lshlrev_b32_e32 v70, 16, v18
	v_and_b32_e32 v71, 0xffff0000, v18
	v_cvt_pk_bf16_f32 v17, v30, v31
	v_pk_mul_f32 v[30:31], v[32:33], v[70:71]
	v_pk_mul_f32 v[32:33], v[74:75], v[70:71]
	v_cvt_pk_bf16_f32 v30, v30, v31
	v_cvt_pk_bf16_f32 v18, v32, v33
	v_lshlrev_b32_e32 v32, 16, v19
	v_and_b32_e32 v33, 0xffff0000, v19
	v_pk_mul_f32 v[34:35], v[34:35], v[32:33]
	v_pk_mul_f32 v[32:33], v[76:77], v[32:33]
	v_cvt_pk_bf16_f32 v31, v34, v35
	v_cvt_pk_bf16_f32 v19, v32, v33
	s_barrier
	ds_read_b128 v[32:35], v69
	ds_read_b128 v[74:77], v69 offset:64
	v_add_u32_e32 v78, s0, v53
	s_waitcnt lgkmcnt(1)
	v_mfma_f32_16x16x32_bf16 v[32:35], v[32:35], v[20:23], 0
	ds_read_b128 v[70:73], v78
	v_add_u32_e32 v69, s35, v54
	ds_read_b128 v[82:85], v69 offset:64
	s_waitcnt lgkmcnt(2)
	v_mfma_f32_16x16x32_bf16 v[32:35], v[74:77], v[28:31], v[32:35]
	ds_read_b128 v[74:77], v78 offset:64
	ds_read_b128 v[78:81], v86
	s_waitcnt lgkmcnt(3)
	v_mfma_f32_16x16x32_bf16 v[70:73], v[70:73], v[24:27], 0
	s_waitcnt lgkmcnt(1)
	v_mfma_f32_16x16x32_bf16 v[70:73], v[74:77], v[16:19], v[70:73]
	ds_read_b128 v[74:77], v69
	s_waitcnt lgkmcnt(0)
	v_mfma_f32_16x16x32_bf16 v[74:77], v[74:77], v[20:23], 0
	s_nop 4
	v_cndmask_b32_e64 v32, v32, v70, s[42:43]
	v_cndmask_b32_e64 v33, v71, v33, s[46:47]
	v_cndmask_b32_e64 v34, v34, v72, s[50:51]
	v_mfma_f32_16x16x32_bf16 v[74:77], v[82:85], v[28:31], v[74:77]
	ds_read_b128 v[82:85], v86 offset:64
	v_cndmask_b32_e64 v35, v35, v73, s[54:55]
	v_cvt_pk_bf16_f32 v32, v32, v33
	v_mfma_f32_16x16x32_bf16 v[78:81], v[78:81], v[24:27], 0
	v_cvt_pk_bf16_f32 v33, v34, v35
	s_waitcnt lgkmcnt(0)
	v_mfma_f32_16x16x32_bf16 v[78:81], v[82:85], v[16:19], v[78:81]
	v_add_u32_e32 v82, s0, v55
	s_nop 6
	v_cndmask_b32_e64 v69, v74, v78, s[44:45]
	v_cndmask_b32_e64 v70, v75, v79, s[48:49]
	v_cndmask_b32_e64 v71, v76, v80, s[52:53]
	v_cndmask_b32_e64 v72, v77, v81, s[56:57]
	v_cvt_pk_bf16_f32 v34, v69, v70
	v_add_u32_e32 v69, s35, v55
	v_cvt_pk_bf16_f32 v35, v71, v72
	ds_read_b128 v[70:73], v69
	ds_read_b128 v[78:81], v69 offset:64
	s_waitcnt lgkmcnt(1)
	v_mfma_f32_16x16x32_bf16 v[70:73], v[70:73], v[20:23], 0
	ds_read_b128 v[74:77], v82
	v_add_u32_e32 v69, s35, v56
	ds_read_b128 v[86:89], v69 offset:64
	s_waitcnt lgkmcnt(2)
	v_mfma_f32_16x16x32_bf16 v[70:73], v[78:81], v[28:31], v[70:73]
	ds_read_b128 v[78:81], v82 offset:64
	ds_read_b128 v[82:85], v90
	s_waitcnt lgkmcnt(3)
	v_mfma_f32_16x16x32_bf16 v[74:77], v[74:77], v[24:27], 0
	s_waitcnt lgkmcnt(1)
	v_mfma_f32_16x16x32_bf16 v[74:77], v[78:81], v[16:19], v[74:77]
	ds_read_b128 v[78:81], v69
	s_waitcnt lgkmcnt(0)
; #define LAS __attribute__((address_space(3)))
; __device__ __forceinline__ u32x4 pack8(const f32x4 a, const f32x4 b) { u32x4 w; w.x = cvt_pk_bf16(a[0], a[1]); w.y = cvt_pk_bf16(a[2], a[3]); w.z = cvt_pk_bf16(b[0], b[1]); w.w = cvt_pk_bf16(b[2], b[3]); return w; }
; __device__ __forceinline__ f32x4 mfma16(bf16x8 a, bf16x8 b, f32x4 c) { return __builtin_amdgcn_mfma_f32_16x16x32_bf16(a, b, c, 0, 0, 0); }
; __device__ __forceinline__ void gla_g3(LAS unsigned char* lds, const bf16_t* P, const bf16_t* VAT, const bf16_t* DS, const float* BC, const float* gn, bf16_t* MIX) {
;     ...
;             f32x4 p0, p1;
; #pragma unroll
;             for (int ii = 0; ii < 4; ++ii) { const int j0 = 32 * t + 8 * g + ii, j1 = j0 + 4; p0[ii] = (j0 <= iq) ? sf[0][ii] : sv[0][ii]; p1[ii] = (j1 <= iq) ? sf[1][ii] : sv[1][ii]; }
;             pfrag[t] = __builtin_bit_cast(bf16x8, pack8(p0, p1));
;         }
;         f32x4 o[4];
; #pragma unroll
;         for (int mb = 0; mb < 4; ++mb) o[mb] = (f32x4){0.f, 0.f, 0.f, 0.f};
; #pragma unroll
;         for (int t = 0; t < 2; ++t)
; #pragma unroll
;             for (int mb = 0; mb < 4; ++mb) o[mb] = mfma16(*(const LAS bf16x8*)(lds + G3_VT + ((16 * (4 * dvh + mb) + fr) * 9 + 4 * t + g) * 16), pfrag[t], o[mb]);
; #pragma unroll
;         for (int s2 = 0; s2 < 2; ++s2)
; #pragma unroll
;             for (int mb = 0; mb < 4; ++mb) {
;                 o[mb] = mfma16(*(const LAS bf16x8*)(lds + G3_SF + ((16 * (4 * dvh + mb) + fr) * 9 + 4 * s2 + g) * 16), qdf[s2], o[mb]);
;                 o[mb] = mfma16(*(const LAS bf16x8*)(lds + G3_SB + ((16 * (4 * dvh + mb) + fr) * 9 + 4 * s2 + g) * 16), qdb[s2], o[mb]);
;             }
;         float ss = 0.f;
; #pragma unroll
;         for (int mb = 0; mb < 4; ++mb) ss += (o[mb][0] * o[mb][0] + o[mb][1] * o[mb][1]) + (o[mb][2] * o[mb][2] + o[mb][3] * o[mb][3]);
;         ss += __shfl_xor(ss, 16); ss += __shfl_xor(ss, 32);
;         LAS float* red = (LAS float*)(lds + G3_RED);
;         if (g == 0) red[iq * 2 + dvh] = ss;
	v_mfma_f32_16x16x32_bf16 v[78:81], v[78:81], v[20:23], 0
	s_nop 4
	v_cndmask_b32_e64 v69, v70, v74, s[58:59]
	v_cndmask_b32_e64 v70, v71, v75, s[62:63]
	v_cndmask_b32_e64 v71, v72, v76, s[66:67]
	v_mfma_f32_16x16x32_bf16 v[78:81], v[86:89], v[28:31], v[78:81]
	ds_read_b128 v[86:89], v90 offset:64
	v_cndmask_b32_e64 v72, v73, v77, s[70:71]
	v_cvt_pk_bf16_f32 v71, v71, v72
	v_mfma_f32_16x16x32_bf16 v[82:85], v[82:85], v[24:27], 0
	v_cvt_pk_bf16_f32 v70, v69, v70
	s_waitcnt lgkmcnt(0)
	v_mfma_f32_16x16x32_bf16 v[82:85], v[86:89], v[16:19], v[82:85]
	ds_read_b128 v[86:89], v64 offset:9216
	s_nop 6
	v_cndmask_b32_e64 v74, v78, v82, s[60:61]
	v_cndmask_b32_e64 v75, v79, v83, s[64:65]
	v_cndmask_b32_e64 v76, v80, v84, s[68:69]
	v_cndmask_b32_e64 v73, v81, v85, s[72:73]
	v_cvt_pk_bf16_f32 v72, v74, v75
	v_cvt_pk_bf16_f32 v73, v76, v73
	ds_read_b128 v[74:77], v61 offset:9216
	ds_read_b128 v[78:81], v62 offset:9216
	ds_read_b128 v[82:85], v63 offset:9216
	s_waitcnt lgkmcnt(2)
	v_mfma_f32_16x16x32_bf16 v[74:77], v[74:77], v[32:35], 0
	s_waitcnt lgkmcnt(1)
	v_mfma_f32_16x16x32_bf16 v[78:81], v[78:81], v[32:35], 0
	s_waitcnt lgkmcnt(0)
	v_mfma_f32_16x16x32_bf16 v[82:85], v[82:85], v[32:35], 0
	v_mfma_f32_16x16x32_bf16 v[32:35], v[86:89], v[32:35], 0
	ds_read_b128 v[86:89], v65 offset:9216
	s_waitcnt lgkmcnt(0)
	v_mfma_f32_16x16x32_bf16 v[74:77], v[86:89], v[70:73], v[74:77]
	ds_read_b128 v[86:89], v66 offset:9216
	s_waitcnt lgkmcnt(0)
	v_mfma_f32_16x16x32_bf16 v[78:81], v[86:89], v[70:73], v[78:81]
	ds_read_b128 v[86:89], v67 offset:9216
	s_waitcnt lgkmcnt(0)
	v_mfma_f32_16x16x32_bf16 v[82:85], v[86:89], v[70:73], v[82:85]
	ds_read_b128 v[86:89], v68 offset:9216
	s_waitcnt lgkmcnt(0)
	v_mfma_f32_16x16x32_bf16 v[32:35], v[86:89], v[70:73], v[32:35]
	ds_read_b128 v[70:73], v61 offset:27648
	s_waitcnt lgkmcnt(0)
	v_mfma_f32_16x16x32_bf16 v[70:73], v[70:73], v[20:23], v[74:77]
	s_nop 2
	ds_read_b128 v[74:77], v61 offset:46080
	s_waitcnt lgkmcnt(0)
	v_mfma_f32_16x16x32_bf16 v[70:73], v[74:77], v[24:27], v[70:73]
	ds_read_b128 v[74:77], v62 offset:27648
	s_waitcnt lgkmcnt(0)
	v_mfma_f32_16x16x32_bf16 v[74:77], v[74:77], v[20:23], v[78:81]
	s_nop 2
	ds_read_b128 v[78:81], v62 offset:46080
	s_waitcnt lgkmcnt(0)
	v_mfma_f32_16x16x32_bf16 v[74:77], v[78:81], v[24:27], v[74:77]
	ds_read_b128 v[78:81], v63 offset:27648
	s_waitcnt lgkmcnt(0)
	v_mfma_f32_16x16x32_bf16 v[78:81], v[78:81], v[20:23], v[82:85]
	s_nop 2
	ds_read_b128 v[82:85], v63 offset:46080
	s_waitcnt lgkmcnt(0)
	v_mfma_f32_16x16x32_bf16 v[78:81], v[82:85], v[24:27], v[78:81]
	ds_read_b128 v[82:85], v64 offset:27648
	s_waitcnt lgkmcnt(0)
	v_mfma_f32_16x16x32_bf16 v[20:23], v[82:85], v[20:23], v[32:35]
	s_nop 2
	ds_read_b128 v[32:35], v64 offset:46080
	s_waitcnt lgkmcnt(0)
	v_mfma_f32_16x16x32_bf16 v[82:85], v[32:35], v[24:27], v[20:23]
	s_nop 2
	ds_read_b128 v[20:23], v65 offset:27648
	ds_read_b128 v[24:27], v65 offset:46080
	s_waitcnt lgkmcnt(1)
	v_mfma_f32_16x16x32_bf16 v[20:23], v[20:23], v[28:31], v[70:73]
	s_nop 2
	ds_read_b128 v[70:73], v67 offset:46080
	s_waitcnt lgkmcnt(1)
	v_mfma_f32_16x16x32_bf16 v[32:35], v[24:27], v[16:19], v[20:23]
	ds_read_b128 v[24:27], v66 offset:46080
	s_nop 1
	ds_read_b128 v[20:23], v66 offset:27648
	s_waitcnt lgkmcnt(0)
	v_mfma_f32_16x16x32_bf16 v[20:23], v[20:23], v[28:31], v[74:77]
	v_mfma_f32_16x16x32_bf16 v[24:27], v[24:27], v[16:19], v[20:23]
	s_nop 6
	ds_read_b128 v[20:23], v67 offset:27648
	s_waitcnt lgkmcnt(0)
	v_mfma_f32_16x16x32_bf16 v[20:23], v[20:23], v[28:31], v[78:81]
	v_mfma_f32_16x16x32_bf16 v[20:23], v[70:73], v[16:19], v[20:23]
	ds_read_b128 v[70:73], v68 offset:27648
	s_waitcnt lgkmcnt(0)
	v_mfma_f32_16x16x32_bf16 v[28:31], v[70:73], v[28:31], v[82:85]
	ds_read_b128 v[70:73], v68 offset:46080
	s_waitcnt lgkmcnt(0)
	v_mfma_f32_16x16x32_bf16 v[16:19], v[70:73], v[16:19], v[28:31]
	s_nop 4
	v_mul_f32_e32 v28, v33, v33
	v_mul_f32_e32 v29, v35, v35
	v_fmac_f32_e32 v28, v32, v32
	v_fmac_f32_e32 v29, v34, v34
	v_add_f32_e32 v28, v28, v29
	v_mul_f32_e32 v29, v25, v25
	v_mul_f32_e32 v30, v27, v27
	v_fmac_f32_e32 v29, v24, v24
	v_fmac_f32_e32 v30, v26, v26
	v_add_f32_e32 v29, v29, v30
	v_add_f32_e32 v28, v28, v29
	v_mul_f32_e32 v29, v21, v21
	v_mul_f32_e32 v30, v23, v23
	v_fmac_f32_e32 v29, v20, v20
	v_fmac_f32_e32 v30, v22, v22
	v_add_f32_e32 v29, v29, v30
	v_add_f32_e32 v28, v28, v29
	v_mul_f32_e32 v29, v17, v17
	v_mul_f32_e32 v30, v19, v19
	v_fmac_f32_e32 v29, v16, v16
	v_fmac_f32_e32 v30, v18, v18
	v_add_f32_e32 v29, v29, v30
	v_add_f32_e32 v28, v28, v29
	v_xor_b32_e32 v29, 16, v231
	v_cmp_lt_i32_e32 vcc, v29, v232
	s_nop 1
	v_cndmask_b32_e32 v29, v231, v29, vcc
	v_lshlrev_b32_e32 v29, 2, v29
	ds_bpermute_b32 v29, v29, v28
	s_waitcnt lgkmcnt(0)
	v_add_f32_e32 v28, v28, v29
	v_xor_b32_e32 v29, 32, v231
	v_cmp_lt_i32_e32 vcc, v29, v232
	s_nop 1
	v_cndmask_b32_e32 v29, v231, v29, vcc
	v_lshlrev_b32_e32 v29, 2, v29
	ds_bpermute_b32 v29, v29, v28
	s_and_saveexec_b64 s[0:1], s[40:41]
	s_cbranch_execz .LBB0_631
	s_waitcnt lgkmcnt(0)
	v_add_f32_e32 v28, v28, v29
	v_add_u32_e32 v29, s16, v52
	ds_write_b32 v29, v28
